# LayerNorm phases: per-row modulation shift/scale loads (8 serialized L2 round trips per row) issued with the row's residual loads at the top of the step
# speedup vs baseline: 1.0128x; 1.0090x over previous
; __global__ void __launch_bounds__(512, 2) mk_fwd(Args args) {
;     ...
;                 for (int row0 = rbeg + wstart; row0 < rend; row0 += 2 * wstride) {
;                     const int row1 = row0 + wstride; const bool has1 = row1 < rend;
;                     f32x4 va[4], vb[4];
; #pragma unroll
;                     for (int j = 0; j < 4; ++j) vb[j] = (f32x4){0.f, 0.f, 0.f, 0.f};
;                     { const float* xp = (row0 < ML) ? XL + (size_t)row0 * DM : XC + (size_t)(row0 - ML) * DM;
; #pragma unroll
;                       for (int j = 0; j < 4; ++j) va[j] = *(const f32x4*)(xp + 4 * lane + 256 * j); }
;                     if (has1) { const float* xp = (row1 < ML) ? XL + (size_t)row1 * DM : XC + (size_t)(row1 - ML) * DM;
; #pragma unroll
;                       for (int j = 0; j < 4; ++j) vb[j] = *(const f32x4*)(xp + 4 * lane + 256 * j); }
;                     ln_row(row0, va);
;                     if (has1) ln_row(row1, vb);
.LBB0_816:
	v_lshlrev_b32_e32 v0, 2, v34
	v_lshl_add_u64 v[2:3], s[4:5], 0, v[0:1]
	flat_load_dwordx4 v[30:33], v[2:3]
	flat_load_dwordx4 v[26:29], v[2:3] offset:1024
	flat_load_dwordx4 v[22:25], v[2:3] offset:2048
	flat_load_dwordx4 v[18:21], v[2:3] offset:3072
	s_min_i32 s20, s17, 0x8000
	s_ashr_i32 s20, s20, 11
	s_mul_hi_i32 s26, s20, 0x6000
	s_mulk_i32 s20, 0x6000
	s_add_u32 s50, s11, s20
	s_addc_u32 s51, s14, s26
	v_lshl_add_u64 v[70:71], s[50:51], 0, v[0:1]
	s_mov_b64 s[50:51], 0x1000
	v_lshl_add_u64 v[72:73], s[50:51], 0, v[70:71]
	global_load_dwordx4 v[74:77], v[70:71], off
	global_load_dwordx4 v[90:93], v[72:73], off
	global_load_dwordx4 v[78:81], v[70:71], off offset:1024
	global_load_dwordx4 v[94:97], v[72:73], off offset:1024
	global_load_dwordx4 v[82:85], v[70:71], off offset:2048
	global_load_dwordx4 v[98:101], v[72:73], off offset:2048
	global_load_dwordx4 v[86:89], v[70:71], off offset:3072
	global_load_dwordx4 v[102:105], v[72:73], off offset:3072
	s_add_i32 s92, s12, s46
	s_add_i32 s90, s92, 0x8000
	s_cmp_lt_i32 s90, s2
	v_mov_b32_e32 v17, 0
	s_cselect_b64 s[94:95], -1, 0
	s_cmp_ge_i32 s90, s2
	v_mov_b32_e32 v16, 0
	v_mov_b32_e32 v15, 0
	v_mov_b32_e32 v14, 0
	v_mov_b32_e32 v5, 0
	v_mov_b32_e32 v4, v17
	v_mov_b32_e32 v3, 0
	v_mov_b32_e32 v2, v17
	v_mov_b32_e32 v9, 0
	v_mov_b32_e32 v8, v17
	v_mov_b32_e32 v7, 0
	v_mov_b32_e32 v6, v17
	v_mov_b32_e32 v13, 0
	v_mov_b32_e32 v12, v17
	v_mov_b32_e32 v11, 0
	v_mov_b32_e32 v10, v17
	v_mov_b32_e32 v53, 0
	v_mov_b32_e32 v52, v17
	v_mov_b32_e32 v55, 0
	v_mov_b32_e32 v54, v17
	s_cbranch_scc1 .LBB0_822
	s_cmpk_gt_i32 s90, 0x7fff
	s_mov_b64 s[50:51], -1
	s_cbranch_scc0 .LBB0_819
	s_mov_b32 s93, s47
	s_lshl_b64 s[4:5], s[92:93], 12
	s_add_u32 s4, s40, s4
	s_addc_u32 s5, s41, s5
	s_mov_b64 s[50:51], 0

; __global__ void __launch_bounds__(512, 2) mk_fwd(Args args) {
;     ...
;                 for (int row0 = rbeg + wstart; row0 < rend; row0 += 2 * wstride) {
;                     const int row1 = row0 + wstride; const bool has1 = row1 < rend;
;                     f32x4 va[4], vb[4];
; #pragma unroll
;                     for (int j = 0; j < 4; ++j) vb[j] = (f32x4){0.f, 0.f, 0.f, 0.f};
;                     { const float* xp = (row0 < ML) ? XL + (size_t)row0 * DM : XC + (size_t)(row0 - ML) * DM;
; #pragma unroll
;                       for (int j = 0; j < 4; ++j) va[j] = *(const f32x4*)(xp + 4 * lane + 256 * j); }
;                     if (has1) { const float* xp = (row1 < ML) ? XL + (size_t)row1 * DM : XC + (size_t)(row1 - ML) * DM;
; #pragma unroll
;                       for (int j = 0; j < 4; ++j) vb[j] = *(const f32x4*)(xp + 4 * lane + 256 * j); }
;                     ln_row(row0, va);
;                     if (has1) ln_row(row1, vb);
.LBB0_821:
	v_lshl_add_u64 v[6:7], s[4:5], 0, v[0:1]
	flat_load_dwordx4 v[14:17], v[6:7] offset:3072
	flat_load_dwordx4 v[2:5], v[6:7] offset:2048
	flat_load_dwordx4 v[10:13], v[6:7]
	s_nop 0
	flat_load_dwordx4 v[6:9], v[6:7] offset:1024
	s_min_i32 s20, s90, 0x8000
	s_ashr_i32 s20, s20, 11
	s_mul_hi_i32 s26, s20, 0x6000
	s_mulk_i32 s20, 0x6000
	s_add_u32 s50, s11, s20
	s_addc_u32 s51, s14, s26
	v_lshl_add_u64 v[70:71], s[50:51], 0, v[0:1]
	s_mov_b64 s[50:51], 0x1000
	v_lshl_add_u64 v[72:73], s[50:51], 0, v[70:71]
	global_load_dwordx4 v[106:109], v[70:71], off
	global_load_dwordx4 v[122:125], v[72:73], off
	global_load_dwordx4 v[110:113], v[70:71], off offset:1024
	global_load_dwordx4 v[126:129], v[72:73], off offset:1024
	global_load_dwordx4 v[114:117], v[70:71], off offset:2048
	global_load_dwordx4 v[130:133], v[72:73], off offset:2048
	global_load_dwordx4 v[118:121], v[70:71], off offset:3072
	global_load_dwordx4 v[134:137], v[72:73], off offset:3072
	s_waitcnt vmcnt(0) lgkmcnt(0)
	v_mov_b32_e32 v53, v17
	v_mov_b32_e32 v52, v16
	v_mov_b32_e32 v55, v15
	v_mov_b32_e32 v54, v14

; __device__ __forceinline__ unsigned cvt_pk_bf16(float lo, float hi) { unsigned r; asm("v_cvt_pk_bf16_f32 %0, %1, %2" : "=v"(r) : "v"(lo), "v"(hi)); return r; }
; __global__ void __launch_bounds__(512, 2) mk_fwd(Args args) {
;     ...
;                     for (int j = 0; j < 4; ++j) { const int col = 4 * lane + 256 * j; const f32x4 y = v[j] * rstd;
;                         if (lastln) *(f32x4*)(xr + col) = y;
;                         if (!lastln) { const f32x4 sh = *(const f32x4*)(mp + col), sc = *(const f32x4*)(mp + 1024 + col); const f32x4 hv = y * (sc + 1.0f) + sh;
;                             u32x2 w; w.x = cvt_pk_bf16(hv[0], hv[1]); w.y = cvt_pk_bf16(hv[2], hv[3]); *(u32x2*)(HO + (size_t)row * DM + col) = w; } }
.LBB0_824:
	s_or_b64 exec, exec, s[4:5]
	s_and_b64 s[4:5], s[48:49], exec
	v_readlane_b32 s64, v252, 0
	s_cselect_b32 s5, s7, 0
	s_cselect_b32 s4, s6, s46
	v_readlane_b32 s76, v252, 12
	v_readlane_b32 s77, v252, 13
	s_cselect_b32 s18, s77, s41
	s_cselect_b32 s19, s76, s40
	s_lshl_b64 s[4:5], s[4:5], 12
	s_add_u32 s4, s19, s4
	s_addc_u32 s5, s18, s5
	s_min_i32 s17, s17, 0x8000
	s_ashr_i32 s17, s17, 11
	s_mul_hi_i32 s18, s17, 0x6000
	s_mulk_i32 s17, 0x6000
	s_add_u32 s48, s11, s17
	s_addc_u32 s49, s14, s18
	v_readlane_b32 s18, v254, 36
	s_add_u32 s50, s48, 0x1000
	v_readlane_b32 s19, v254, 37
	s_addc_u32 s51, s49, 0
	v_pk_mul_f32 v[32:33], v[32:33], v[56:57] op_sel_hi:[1,0]
	v_pk_mul_f32 v[30:31], v[30:31], v[56:57] op_sel_hi:[1,0]
	s_mov_b64 s[52:53], -1
	s_and_b64 vcc, exec, s[8:9]
	v_lshl_add_u64 v[58:59], s[18:19], 0, v[50:51]
	v_readlane_b32 s65, v252, 1
	v_readlane_b32 s66, v252, 2
	v_readlane_b32 s67, v252, 3
	v_readlane_b32 s68, v252, 4
	v_readlane_b32 s69, v252, 5
	v_readlane_b32 s70, v252, 6
	v_readlane_b32 s71, v252, 7
	v_readlane_b32 s72, v252, 8
	v_readlane_b32 s73, v252, 9
	v_readlane_b32 s74, v252, 10
	v_readlane_b32 s75, v252, 11
	v_readlane_b32 s78, v252, 14
	v_readlane_b32 s79, v252, 15
	s_cbranch_vccz .LBB0_826
	v_lshl_add_u64 v[66:67], s[50:51], 0, v[0:1]
	v_lshl_add_u64 v[62:63], s[48:49], 0, v[0:1]
	v_mov_b64_e32 v[66:67], v[90:91]
	v_mov_b64_e32 v[68:69], v[92:93]
	s_mov_b64 s[52:53], 0
	v_mov_b64_e32 v[62:63], v[74:75]
	v_mov_b64_e32 v[64:65], v[76:77]
	s_waitcnt lgkmcnt(0)
	v_pk_add_f32 v[68:69], v[68:69], 1.0 op_sel_hi:[1,0]
	v_pk_add_f32 v[66:67], v[66:67], 1.0 op_sel_hi:[1,0]
	v_pk_fma_f32 v[64:65], v[32:33], v[68:69], v[64:65]
	v_pk_fma_f32 v[62:63], v[30:31], v[66:67], v[62:63]
	s_nop 0
	v_cvt_pk_bf16_f32 v62, v62, v63
	v_cvt_pk_bf16_f32 v63, v64, v65
	v_add_co_u32_e32 v64, vcc, 0x7000000, v58
	s_nop 1
	v_addc_co_u32_e32 v65, vcc, 0, v59, vcc
	flat_store_dwordx2 v[64:65], v[62:63]

; __device__ __forceinline__ unsigned cvt_pk_bf16(float lo, float hi) { unsigned r; asm("v_cvt_pk_bf16_f32 %0, %1, %2" : "=v"(r) : "v"(lo), "v"(hi)); return r; }
; __global__ void __launch_bounds__(512, 2) mk_fwd(Args args) {
;     ...
;                     for (int j = 0; j < 4; ++j) { const int col = 4 * lane + 256 * j; const f32x4 y = v[j] * rstd;
;                         if (lastln) *(f32x4*)(xr + col) = y;
;                         if (!lastln) { const f32x4 sh = *(const f32x4*)(mp + col), sc = *(const f32x4*)(mp + 1024 + col); const f32x4 hv = y * (sc + 1.0f) + sh;
;                             u32x2 w; w.x = cvt_pk_bf16(hv[0], hv[1]); w.y = cvt_pk_bf16(hv[2], hv[3]); *(u32x2*)(HO + (size_t)row * DM + col) = w; } }
.LBB0_828:
	v_mov_b32_e32 v57, v56
	s_nop 0
	v_mov_b32_e32 v30, v56
	v_mov_b32_e32 v31, v56
	v_pk_mul_f32 v[28:29], v[28:29], v[30:31]
	v_pk_mul_f32 v[26:27], v[26:27], v[56:57]
	s_mov_b64 s[52:53], -1
	s_and_b64 vcc, exec, s[8:9]
	s_cbranch_vccz .LBB0_830
	v_lshlrev_b32_e32 v62, 2, v38
	v_mov_b32_e32 v63, v1
	v_lshl_add_u64 v[62:63], s[50:51], 0, v[62:63]
	v_lshl_add_u64 v[30:31], s[48:49], 0, v[0:1]
	v_mov_b64_e32 v[62:63], v[94:95]
	v_mov_b64_e32 v[64:65], v[96:97]
	s_mov_b64 s[52:53], 0
	v_mov_b64_e32 v[30:31], v[78:79]
	v_mov_b64_e32 v[32:33], v[80:81]
	s_waitcnt lgkmcnt(0)
	v_pk_add_f32 v[64:65], v[64:65], 1.0 op_sel_hi:[1,0]
	v_pk_add_f32 v[62:63], v[62:63], 1.0 op_sel_hi:[1,0]
	v_pk_fma_f32 v[32:33], v[28:29], v[64:65], v[32:33]
	v_pk_fma_f32 v[30:31], v[26:27], v[62:63], v[30:31]
	s_nop 0
	v_cvt_pk_bf16_f32 v30, v30, v31
	v_cvt_pk_bf16_f32 v31, v32, v33
	v_add_co_u32_e32 v32, vcc, 0x7000000, v58
	s_nop 1
	v_addc_co_u32_e32 v33, vcc, 0, v59, vcc
	flat_store_dwordx2 v[32:33], v[30:31] offset:512

; __device__ __forceinline__ unsigned cvt_pk_bf16(float lo, float hi) { unsigned r; asm("v_cvt_pk_bf16_f32 %0, %1, %2" : "=v"(r) : "v"(lo), "v"(hi)); return r; }
; __global__ void __launch_bounds__(512, 2) mk_fwd(Args args) {
;     ...
;                     for (int j = 0; j < 4; ++j) { const int col = 4 * lane + 256 * j; const f32x4 y = v[j] * rstd;
;                         if (lastln) *(f32x4*)(xr + col) = y;
;                         if (!lastln) { const f32x4 sh = *(const f32x4*)(mp + col), sc = *(const f32x4*)(mp + 1024 + col); const f32x4 hv = y * (sc + 1.0f) + sh;
;                             u32x2 w; w.x = cvt_pk_bf16(hv[0], hv[1]); w.y = cvt_pk_bf16(hv[2], hv[3]); *(u32x2*)(HO + (size_t)row * DM + col) = w; } }
.LBB0_832:
	s_nop 1
	v_mov_b32_e32 v26, v56
	v_mov_b32_e32 v27, v56
	v_pk_mul_f32 v[24:25], v[24:25], v[26:27]
	v_pk_mul_f32 v[22:23], v[22:23], v[56:57]
	s_mov_b64 s[52:53], -1
	s_and_b64 vcc, exec, s[8:9]
	s_cbranch_vccz .LBB0_834
	v_lshlrev_b32_e32 v30, 2, v40
	v_mov_b32_e32 v31, v1
	v_lshl_add_u64 v[30:31], s[50:51], 0, v[30:31]
	v_lshl_add_u64 v[26:27], s[48:49], 0, v[0:1]
	v_mov_b64_e32 v[30:31], v[98:99]
	v_mov_b64_e32 v[32:33], v[100:101]
	s_mov_b64 s[52:53], 0
	v_mov_b64_e32 v[26:27], v[82:83]
	v_mov_b64_e32 v[28:29], v[84:85]
	s_waitcnt lgkmcnt(0)
	v_pk_add_f32 v[32:33], v[32:33], 1.0 op_sel_hi:[1,0]
	v_pk_add_f32 v[30:31], v[30:31], 1.0 op_sel_hi:[1,0]
	v_pk_fma_f32 v[28:29], v[24:25], v[32:33], v[28:29]
	v_pk_fma_f32 v[26:27], v[22:23], v[30:31], v[26:27]
	s_nop 0
	v_cvt_pk_bf16_f32 v26, v26, v27
	v_cvt_pk_bf16_f32 v27, v28, v29
	v_add_co_u32_e32 v28, vcc, 0x7000000, v58
	s_nop 1
	v_addc_co_u32_e32 v29, vcc, 0, v59, vcc
	flat_store_dwordx2 v[28:29], v[26:27] offset:1024

; __device__ __forceinline__ unsigned cvt_pk_bf16(float lo, float hi) { unsigned r; asm("v_cvt_pk_bf16_f32 %0, %1, %2" : "=v"(r) : "v"(lo), "v"(hi)); return r; }
; __global__ void __launch_bounds__(512, 2) mk_fwd(Args args) {
;     ...
;                     for (int j = 0; j < 4; ++j) { const int col = 4 * lane + 256 * j; const f32x4 y = v[j] * rstd;
;                         if (lastln) *(f32x4*)(xr + col) = y;
;                         if (!lastln) { const f32x4 sh = *(const f32x4*)(mp + col), sc = *(const f32x4*)(mp + 1024 + col); const f32x4 hv = y * (sc + 1.0f) + sh;
;                             u32x2 w; w.x = cvt_pk_bf16(hv[0], hv[1]); w.y = cvt_pk_bf16(hv[2], hv[3]); *(u32x2*)(HO + (size_t)row * DM + col) = w; } }
.LBB0_839:
	v_lshlrev_b32_e32 v22, 2, v42
	v_mov_b32_e32 v23, v1
	v_lshl_add_u64 v[22:23], s[50:51], 0, v[22:23]
	v_mov_b64_e32 v[22:23], v[102:103]
	v_mov_b64_e32 v[24:25], v[104:105]
	v_lshl_add_u64 v[26:27], s[48:49], 0, v[0:1]
	v_mov_b64_e32 v[26:27], v[86:87]
	v_mov_b64_e32 v[28:29], v[88:89]
	v_add_co_u32_e32 v30, vcc, 0x7000000, v58
	s_nop 1
	v_addc_co_u32_e32 v31, vcc, 0, v59, vcc
	s_waitcnt lgkmcnt(0)
	v_pk_add_f32 v[22:23], v[22:23], 1.0 op_sel_hi:[1,0]
	v_pk_add_f32 v[24:25], v[24:25], 1.0 op_sel_hi:[1,0]
	v_pk_fma_f32 v[22:23], v[18:19], v[22:23], v[26:27]
	v_pk_fma_f32 v[24:25], v[20:21], v[24:25], v[28:29]
	v_cvt_pk_bf16_f32 v22, v22, v23
	s_nop 0
	v_cvt_pk_bf16_f32 v23, v24, v25
	flat_store_dwordx2 v[30:31], v[22:23] offset:1536
	s_cbranch_execnz .LBB0_838

; __device__ __forceinline__ unsigned cvt_pk_bf16(float lo, float hi) { unsigned r; asm("v_cvt_pk_bf16_f32 %0, %1, %2" : "=v"(r) : "v"(lo), "v"(hi)); return r; }
; __global__ void __launch_bounds__(512, 2) mk_fwd(Args args) {
;     ...
;                     for (int j = 0; j < 4; ++j) { const int col = 4 * lane + 256 * j; const f32x4 y = v[j] * rstd;
;                         if (lastln) *(f32x4*)(xr + col) = y;
;                         if (!lastln) { const f32x4 sh = *(const f32x4*)(mp + col), sc = *(const f32x4*)(mp + 1024 + col); const f32x4 hv = y * (sc + 1.0f) + sh;
;                             u32x2 w; w.x = cvt_pk_bf16(hv[0], hv[1]); w.y = cvt_pk_bf16(hv[2], hv[3]); *(u32x2*)(HO + (size_t)row * DM + col) = w; } }
.LBB0_843:
	s_or_b64 exec, exec, s[4:5]
	s_cmp_lt_i32 s90, 0x8000
	v_readlane_b32 s64, v252, 0
	s_cselect_b32 s5, s91, 0
	s_cselect_b32 s4, s90, s92
	v_readlane_b32 s76, v252, 12
	v_readlane_b32 s77, v252, 13
	s_cselect_b32 s17, s77, s41
	s_cselect_b32 s18, s76, s40
	s_lshl_b64 s[4:5], s[4:5], 12
	s_add_u32 s4, s18, s4
	s_addc_u32 s5, s17, s5
	s_min_i32 s17, s90, 0x8000
	s_ashr_i32 s17, s17, 11
	s_mul_hi_i32 s18, s17, 0x6000
	s_mulk_i32 s17, 0x6000
	s_add_u32 s52, s11, s17
	s_addc_u32 s53, s14, s18
	s_add_u32 s50, s52, 0x1000
	s_addc_u32 s51, s53, 0
	s_lshl_b64 s[48:49], s[90:91], 11
	v_pk_mul_f32 v[12:13], v[12:13], v[14:15] op_sel_hi:[1,0]
	v_pk_mul_f32 v[10:11], v[10:11], v[14:15] op_sel_hi:[1,0]
	s_mov_b64 s[54:55], -1
	s_and_b64 vcc, exec, s[8:9]
	v_readlane_b32 s65, v252, 1
	v_readlane_b32 s66, v252, 2
	v_readlane_b32 s67, v252, 3
	v_readlane_b32 s68, v252, 4
	v_readlane_b32 s69, v252, 5
	v_readlane_b32 s70, v252, 6
	v_readlane_b32 s71, v252, 7
	v_readlane_b32 s72, v252, 8
	v_readlane_b32 s73, v252, 9
	v_readlane_b32 s74, v252, 10
	v_readlane_b32 s75, v252, 11
	v_readlane_b32 s78, v252, 14
	v_readlane_b32 s79, v252, 15
	s_cbranch_vccz .LBB0_845
	v_lshl_add_u64 v[20:21], s[50:51], 0, v[0:1]
	v_lshl_add_u64 v[16:17], s[52:53], 0, v[0:1]
	v_mov_b64_e32 v[20:21], v[122:123]
	v_mov_b64_e32 v[22:23], v[124:125]
	s_mov_b64 s[54:55], 0
	v_mov_b64_e32 v[16:17], v[106:107]
	v_mov_b64_e32 v[18:19], v[108:109]
	s_waitcnt lgkmcnt(0)
	v_pk_add_f32 v[22:23], v[22:23], 1.0 op_sel_hi:[1,0]
	v_pk_add_f32 v[20:21], v[20:21], 1.0 op_sel_hi:[1,0]
	v_pk_fma_f32 v[18:19], v[12:13], v[22:23], v[18:19]
	v_pk_fma_f32 v[16:17], v[10:11], v[20:21], v[16:17]
	s_nop 0
	v_cvt_pk_bf16_f32 v16, v16, v17
	v_cvt_pk_bf16_f32 v17, v18, v19
	v_lshl_add_u64 v[18:19], v[36:37], 0, s[48:49]
	flat_store_dwordx2 v[18:19], v[16:17]

; __device__ __forceinline__ unsigned cvt_pk_bf16(float lo, float hi) { unsigned r; asm("v_cvt_pk_bf16_f32 %0, %1, %2" : "=v"(r) : "v"(lo), "v"(hi)); return r; }
; __global__ void __launch_bounds__(512, 2) mk_fwd(Args args) {
;     ...
;                     for (int j = 0; j < 4; ++j) { const int col = 4 * lane + 256 * j; const f32x4 y = v[j] * rstd;
;                         if (lastln) *(f32x4*)(xr + col) = y;
;                         if (!lastln) { const f32x4 sh = *(const f32x4*)(mp + col), sc = *(const f32x4*)(mp + 1024 + col); const f32x4 hv = y * (sc + 1.0f) + sh;
;                             u32x2 w; w.x = cvt_pk_bf16(hv[0], hv[1]); w.y = cvt_pk_bf16(hv[2], hv[3]); *(u32x2*)(HO + (size_t)row * DM + col) = w; } }
.LBB0_847:
	v_mov_b32_e32 v15, v14
	s_nop 0
	v_mov_b32_e32 v10, v14
	v_mov_b32_e32 v11, v14
	v_pk_mul_f32 v[8:9], v[8:9], v[10:11]
	v_pk_mul_f32 v[6:7], v[6:7], v[14:15]
	s_mov_b64 s[54:55], -1
	s_and_b64 vcc, exec, s[8:9]
	s_cbranch_vccz .LBB0_849
	v_lshlrev_b32_e32 v16, 2, v38
	v_mov_b32_e32 v17, v1
	v_lshl_add_u64 v[16:17], s[50:51], 0, v[16:17]
	v_lshl_add_u64 v[10:11], s[52:53], 0, v[0:1]
	v_mov_b64_e32 v[16:17], v[126:127]
	v_mov_b64_e32 v[18:19], v[128:129]
	s_mov_b64 s[54:55], 0
	v_mov_b64_e32 v[10:11], v[110:111]
	v_mov_b64_e32 v[12:13], v[112:113]
	s_waitcnt lgkmcnt(0)
	v_pk_add_f32 v[18:19], v[18:19], 1.0 op_sel_hi:[1,0]
	v_pk_add_f32 v[16:17], v[16:17], 1.0 op_sel_hi:[1,0]
	v_pk_fma_f32 v[12:13], v[8:9], v[18:19], v[12:13]
	v_pk_fma_f32 v[10:11], v[6:7], v[16:17], v[10:11]
	s_nop 0
	v_cvt_pk_bf16_f32 v10, v10, v11
	v_cvt_pk_bf16_f32 v11, v12, v13
	v_lshl_add_u64 v[12:13], v[44:45], 0, s[48:49]
	flat_store_dwordx2 v[12:13], v[10:11]

; __device__ __forceinline__ unsigned cvt_pk_bf16(float lo, float hi) { unsigned r; asm("v_cvt_pk_bf16_f32 %0, %1, %2" : "=v"(r) : "v"(lo), "v"(hi)); return r; }
; __global__ void __launch_bounds__(512, 2) mk_fwd(Args args) {
;     ...
;                     for (int j = 0; j < 4; ++j) { const int col = 4 * lane + 256 * j; const f32x4 y = v[j] * rstd;
;                         if (lastln) *(f32x4*)(xr + col) = y;
;                         if (!lastln) { const f32x4 sh = *(const f32x4*)(mp + col), sc = *(const f32x4*)(mp + 1024 + col); const f32x4 hv = y * (sc + 1.0f) + sh;
;                             u32x2 w; w.x = cvt_pk_bf16(hv[0], hv[1]); w.y = cvt_pk_bf16(hv[2], hv[3]); *(u32x2*)(HO + (size_t)row * DM + col) = w; } }
.LBB0_851:
	s_nop 1
	v_mov_b32_e32 v6, v14
	v_mov_b32_e32 v7, v14
	v_pk_mul_f32 v[4:5], v[4:5], v[6:7]
	v_pk_mul_f32 v[2:3], v[2:3], v[14:15]
	s_mov_b64 s[54:55], -1
	s_and_b64 vcc, exec, s[8:9]
	s_cbranch_vccz .LBB0_853
	v_lshlrev_b32_e32 v10, 2, v40
	v_mov_b32_e32 v11, v1
	v_lshl_add_u64 v[10:11], s[50:51], 0, v[10:11]
	v_lshl_add_u64 v[6:7], s[52:53], 0, v[0:1]
	v_mov_b64_e32 v[10:11], v[130:131]
	v_mov_b64_e32 v[12:13], v[132:133]
	s_mov_b64 s[54:55], 0
	v_mov_b64_e32 v[6:7], v[114:115]
	v_mov_b64_e32 v[8:9], v[116:117]
	s_waitcnt lgkmcnt(0)
	v_pk_add_f32 v[12:13], v[12:13], 1.0 op_sel_hi:[1,0]
	v_pk_add_f32 v[10:11], v[10:11], 1.0 op_sel_hi:[1,0]
	v_pk_fma_f32 v[8:9], v[4:5], v[12:13], v[8:9]
	v_pk_fma_f32 v[6:7], v[2:3], v[10:11], v[6:7]
	s_nop 0
	v_cvt_pk_bf16_f32 v6, v6, v7
	v_cvt_pk_bf16_f32 v7, v8, v9
	v_lshl_add_u64 v[8:9], v[46:47], 0, s[48:49]
	flat_store_dwordx2 v[8:9], v[6:7]

; __device__ __forceinline__ unsigned cvt_pk_bf16(float lo, float hi) { unsigned r; asm("v_cvt_pk_bf16_f32 %0, %1, %2" : "=v"(r) : "v"(lo), "v"(hi)); return r; }
; __global__ void __launch_bounds__(512, 2) mk_fwd(Args args) {
;     ...
;                     for (int j = 0; j < 4; ++j) { const int col = 4 * lane + 256 * j; const f32x4 y = v[j] * rstd;
;                         if (lastln) *(f32x4*)(xr + col) = y;
;                         if (!lastln) { const f32x4 sh = *(const f32x4*)(mp + col), sc = *(const f32x4*)(mp + 1024 + col); const f32x4 hv = y * (sc + 1.0f) + sh;
;                             u32x2 w; w.x = cvt_pk_bf16(hv[0], hv[1]); w.y = cvt_pk_bf16(hv[2], hv[3]); *(u32x2*)(HO + (size_t)row * DM + col) = w; } }
.LBB0_855:
	s_nop 1
	v_mov_b32_e32 v2, v14
	v_mov_b32_e32 v3, v14
	v_pk_mul_f32 v[4:5], v[52:53], v[2:3]
	v_pk_mul_f32 v[2:3], v[54:55], v[14:15]
	s_mov_b64 s[54:55], -1
	s_and_b64 vcc, exec, s[8:9]
	s_cbranch_vccz .LBB0_857
	v_lshlrev_b32_e32 v10, 2, v42
	v_mov_b32_e32 v11, v1
	v_lshl_add_u64 v[10:11], s[50:51], 0, v[10:11]
	v_lshl_add_u64 v[6:7], s[52:53], 0, v[0:1]
	v_mov_b64_e32 v[10:11], v[134:135]
	v_mov_b64_e32 v[12:13], v[136:137]
	s_mov_b64 s[54:55], 0
	v_mov_b64_e32 v[6:7], v[118:119]
	v_mov_b64_e32 v[8:9], v[120:121]
	s_waitcnt lgkmcnt(0)
	v_pk_add_f32 v[12:13], v[12:13], 1.0 op_sel_hi:[1,0]
	v_pk_add_f32 v[10:11], v[10:11], 1.0 op_sel_hi:[1,0]
	v_pk_fma_f32 v[8:9], v[4:5], v[12:13], v[8:9]
	v_pk_fma_f32 v[6:7], v[2:3], v[10:11], v[6:7]
	s_nop 0
	v_cvt_pk_bf16_f32 v6, v6, v7
	v_cvt_pk_bf16_f32 v7, v8, v9
	v_lshl_add_u64 v[8:9], v[48:49], 0, s[48:49]
	flat_store_dwordx2 v[8:9], v[6:7]
